# v7 + final RMSNorm gain loads hoisted out of the row loop
# baseline (speedup 1.0000x reference)
; DI int get_tid(int wv) { return launder(wv) * 64 + (int)__builtin_amdgcn_mbcnt_hi(~0u, __builtin_amdgcn_mbcnt_lo(~0u, (unsigned)vlaunder(0))); }
; DI float wave_sum(float v) { v += shx(v, 1); v += shx(v, 2); v += shx(v, 4); v += shx(v, 8); v += shx(v, 16); v += shx(v, 32); return v; }
; DI void phase_final(int wv, float* io  , const float* g, int Mc) {
;     const int tidl = get_tid(wv); const int lane = tidl & 63, wave = tidl >> 6;
;     for (int row = blockIdx.x * 8 + wave; row < Mc; row += gridDim.x * 8) {
;         f32x4* s = (f32x4*)(io + (size_t)row * 1024);
;         f32x4 v[4]; float ss = 0.f;
; #pragma unroll
;         for (int i = 0; i < 4; ++i) { v[i] = s[lane + 64 * i]; ss += v[i][0] * v[i][0] + v[i][1] * v[i][1] + v[i][2] * v[i][2] + v[i][3] * v[i][3]; }
;         ss = wave_sum(ss);
;         const float rstd = 1.0f / sqrtf(ss * (1.f / 1024.f) + EPS);
; #pragma unroll
;         for (int i = 0; i < 4; ++i) { const f32x4 gg = ((const f32x4*)g)[lane + 64 * i]; s[lane + 64 * i] = v[i] * rstd * gg; }
;     }
; }
.LBB0_1622:
	v_xor_b32_e32 v2, 1, v185
	v_cmp_lt_i32_e32 vcc, v2, v197
	s_ashr_i32 s6, s8, 31
	v_readlane_b32 s9, v255, 1
	v_cndmask_b32_e32 v2, v185, v2, vcc
	v_lshlrev_b32_e32 v6, 2, v2
	v_xor_b32_e32 v2, 2, v185
	v_cmp_lt_i32_e32 vcc, v2, v197
	s_mul_hi_u32 s7, s9, s8
	s_mul_i32 s6, s9, s6
	v_cndmask_b32_e32 v2, v185, v2, vcc
	v_lshlrev_b32_e32 v7, 2, v2
	v_xor_b32_e32 v2, 4, v185
	v_cmp_lt_i32_e32 vcc, v2, v197
	s_add_i32 s7, s7, s6
	s_mul_i32 s6, s9, s8
	v_cndmask_b32_e32 v2, v185, v2, vcc
	v_lshlrev_b32_e32 v8, 2, v2
	v_xor_b32_e32 v2, 8, v185
	v_cmp_lt_i32_e32 vcc, v2, v197
	s_lshl_b64 s[6:7], s[6:7], 12
	s_add_u32 s0, s0, s6
	v_cndmask_b32_e32 v2, v185, v2, vcc
	v_lshlrev_b32_e32 v9, 2, v2
	v_xor_b32_e32 v2, 16, v185
	v_cmp_lt_i32_e32 vcc, v2, v197
	v_and_b32_e32 v1, 63, v1
	v_readlane_b32 s12, v254, 0
	v_cndmask_b32_e32 v2, v185, v2, vcc
	v_cmp_lt_i32_e32 vcc, v202, v197
	s_addc_u32 s1, s1, s7
	v_lshlrev_b32_e32 v10, 2, v2
	v_cndmask_b32_e32 v2, v185, v202, vcc
	v_lshlrev_b32_e32 v144, 4, v1
	v_readlane_b32 s22, v254, 10
	v_readlane_b32 s23, v254, 11
	v_lshlrev_b32_e32 v11, 2, v2
	v_lshl_add_u64 v[4:5], s[0:1], 0, v[144:145]
	v_lshl_add_u64 v[2:3], s[22:23], 0, v[144:145]
	s_mov_b64 s[6:7], 0
	v_readlane_b32 s13, v254, 1
	v_readlane_b32 s14, v254, 2
	v_readlane_b32 s15, v254, 3
	v_readlane_b32 s16, v254, 4
	v_readlane_b32 s17, v254, 5
	v_readlane_b32 s18, v254, 6
	v_readlane_b32 s19, v254, 7
	v_readlane_b32 s20, v254, 8
	v_readlane_b32 s21, v254, 9
	v_readlane_b32 s24, v254, 12
	v_readlane_b32 s25, v254, 13
	v_readlane_b32 s26, v254, 14
	v_readlane_b32 s27, v254, 15
	global_load_dwordx4 v[218:221], v[2:3], off
	global_load_dwordx4 v[222:225], v[2:3], off offset:1024
	global_load_dwordx4 v[226:229], v[2:3], off offset:2048
	global_load_dwordx4 v[230:233], v[2:3], off offset:3072
.LBB0_1623:
	v_ashrrev_i32_e32 v1, 31, v0
	v_lshlrev_b64 v[12:13], 12, v[0:1]
	v_lshl_add_u64 v[32:33], v[4:5], 0, v[12:13]
	flat_load_dwordx4 v[12:15], v[32:33]
	flat_load_dwordx4 v[16:19], v[32:33] offset:1024
	flat_load_dwordx4 v[20:23], v[32:33] offset:2048
	flat_load_dwordx4 v[24:27], v[32:33] offset:3072
	s_mov_b32 s0, 0xf800000
	v_add_u32_e32 v0, s43, v0
	s_waitcnt vmcnt(0) lgkmcnt(0)
	v_mul_f32_e32 v1, v13, v13
	v_mul_f32_e32 v42, v17, v17
	v_mov_b32_e32 v36, v21
	v_mov_b32_e32 v37, v25
	v_mov_b32_e32 v34, v20
	v_mov_b32_e32 v35, v24
	v_fmac_f32_e32 v1, v12, v12
	v_fmac_f32_e32 v42, v16, v16
	v_pk_mul_f32 v[36:37], v[36:37], v[36:37]
	v_mov_b32_e32 v38, v22
	v_mov_b32_e32 v39, v26
	v_fmac_f32_e32 v1, v14, v14
	v_fmac_f32_e32 v42, v18, v18
	v_pk_fma_f32 v[34:35], v[34:35], v[34:35], v[36:37]
	v_mov_b32_e32 v40, v23
	v_mov_b32_e32 v41, v27
	v_fmac_f32_e32 v1, v15, v15
	v_fmac_f32_e32 v42, v19, v19
	v_pk_fma_f32 v[34:35], v[38:39], v[38:39], v[34:35]
	v_add_f32_e32 v1, v1, v42
	v_pk_fma_f32 v[34:35], v[40:41], v[40:41], v[34:35]
	s_nop 0
	v_add_f32_e32 v1, v1, v34
	v_add_f32_e32 v1, v1, v35
	ds_bpermute_b32 v34, v6, v1
	s_waitcnt lgkmcnt(0)
	v_add_f32_e32 v1, v1, v34
	ds_bpermute_b32 v34, v7, v1
	s_waitcnt lgkmcnt(0)
	v_add_f32_e32 v1, v1, v34
	ds_bpermute_b32 v34, v8, v1
	s_waitcnt lgkmcnt(0)
	v_add_f32_e32 v1, v1, v34
	ds_bpermute_b32 v34, v9, v1
	s_waitcnt lgkmcnt(0)
	v_add_f32_e32 v1, v1, v34
	ds_bpermute_b32 v34, v10, v1
	s_waitcnt lgkmcnt(0)
	v_add_f32_e32 v1, v1, v34
	ds_bpermute_b32 v34, v11, v1
	s_waitcnt lgkmcnt(0)
	v_add_f32_e32 v1, v1, v34
	v_fmamk_f32 v1, v1, 0x3a800000, v179
	v_mul_f32_e32 v34, 0x4f800000, v1
	v_cmp_gt_f32_e32 vcc, s0, v1
	s_nop 1
	v_cndmask_b32_e32 v1, v1, v34, vcc
	v_sqrt_f32_e32 v34, v1
	s_nop 0
	v_add_u32_e32 v35, -1, v34
	v_add_u32_e32 v36, 1, v34
	v_fma_f32 v37, -v35, v34, v1
	v_fma_f32 v38, -v36, v34, v1
	v_cmp_ge_f32_e64 s[0:1], 0, v37
	s_nop 1
	v_cndmask_b32_e64 v34, v34, v35, s[0:1]
	v_cmp_lt_f32_e64 s[0:1], 0, v38
	s_nop 1
	v_cndmask_b32_e64 v34, v34, v36, s[0:1]
	v_mul_f32_e32 v35, 0x37800000, v34
	v_cndmask_b32_e32 v34, v34, v35, vcc
	v_cmp_class_f32_e32 vcc, v1, v196
	s_nop 1
	v_cndmask_b32_e32 v1, v34, v1, vcc
	v_div_scale_f32 v34, s[0:1], v1, v1, 1.0
	v_rcp_f32_e32 v35, v34
	v_div_scale_f32 v36, vcc, 1.0, v1, 1.0
	v_fma_f32 v37, -v34, v35, 1.0
	v_fmac_f32_e32 v35, v37, v35
	v_mul_f32_e32 v37, v36, v35
	v_fma_f32 v38, -v34, v37, v36
	v_fmac_f32_e32 v37, v38, v35
	v_fma_f32 v34, -v34, v37, v36
	v_div_fmas_f32 v34, v34, v35, v37
	v_div_fixup_f32 v34, v34, v1, 1.0
	v_pk_mul_f32 v[12:13], v[12:13], v[34:35] op_sel_hi:[1,0]
	v_pk_mul_f32 v[14:15], v[14:15], v[34:35] op_sel_hi:[1,0]
	v_pk_mul_f32 v[12:13], v[218:219], v[12:13]
	v_pk_mul_f32 v[14:15], v[220:221], v[14:15]
	flat_store_dwordx4 v[32:33], v[12:15]
	v_pk_mul_f32 v[18:19], v[18:19], v[34:35] op_sel_hi:[1,0]
	v_pk_mul_f32 v[16:17], v[16:17], v[34:35] op_sel_hi:[1,0]
	v_cmp_le_i32_e32 vcc, s8, v0
	s_or_b64 s[6:7], vcc, s[6:7]
	v_pk_mul_f32 v[12:13], v[222:223], v[16:17]
	v_pk_mul_f32 v[14:15], v[224:225], v[18:19]
	flat_store_dwordx4 v[32:33], v[12:15] offset:1024
	v_pk_mul_f32 v[16:17], v[22:23], v[34:35] op_sel_hi:[1,0]
	v_pk_mul_f32 v[18:19], v[20:21], v[34:35] op_sel_hi:[1,0]
	s_nop 0
	v_pk_mul_f32 v[14:15], v[228:229], v[16:17]
	v_pk_mul_f32 v[12:13], v[226:227], v[18:19]
	flat_store_dwordx4 v[32:33], v[12:15] offset:2048
	v_pk_mul_f32 v[16:17], v[26:27], v[34:35] op_sel_hi:[1,0]
	v_pk_mul_f32 v[18:19], v[24:25], v[34:35] op_sel_hi:[1,0]
	s_nop 0
	v_pk_mul_f32 v[14:15], v[232:233], v[16:17]
	v_pk_mul_f32 v[12:13], v[230:231], v[18:19]
	flat_store_dwordx4 v[32:33], v[12:15] offset:3072
	s_andn2_b64 exec, exec, s[6:7]
	s_cbranch_execnz .LBB0_1623
	s_getpc_b64 s[98:99]
